# P7 fused RMSNorm: the agent acquire after the row-panel counter is dropped (part 2 reads only sc1 row sums and the immutable norm_f vector)
# speedup vs baseline: 1.0173x; 1.0039x over previous
.LBB0_1033:
	s_or_b64 exec, exec, s[24:25]
	s_waitcnt vmcnt(0) lgkmcnt(0)
	s_nop 0
	s_barrier
	global_load_dword v156, v[144:145], off sc1
	v_lshlrev_b64 v[154:155], 2, v[148:149]
	v_lshl_add_u64 v[148:149], s[88:89], 0, v[154:155]
	global_load_dwordx4 v[176:179], v[148:149], off
	v_lshlrev_b64 v[146:147], 13, v[146:147]
	v_lshl_add_u64 v[146:147], s[90:91], 0, v[146:147]
	v_lshl_add_u64 v[146:147], v[146:147], 0, v[154:155]
	s_waitcnt vmcnt(1)
	v_fmamk_f32 v156, v156, 0x3a000000, v189
	v_rsq_f32_e32 v156, v156
	s_nop 0
	v_pk_mul_f32 v[72:73], v[72:73], v[156:157] op_sel_hi:[1,0]
	v_pk_mul_f32 v[74:75], v[74:75], v[156:157] op_sel_hi:[1,0]
	s_waitcnt vmcnt(0)
	v_pk_mul_f32 v[72:73], v[176:177], v[72:73]
	v_pk_mul_f32 v[74:75], v[178:179], v[74:75]
	global_store_dwordx4 v[146:147], v[72:75], off
	global_load_dwordx4 v[72:75], v[148:149], off offset:16
	v_pk_mul_f32 v[76:77], v[76:77], v[156:157] op_sel_hi:[1,0]
	v_pk_mul_f32 v[78:79], v[78:79], v[156:157] op_sel_hi:[1,0]
	s_waitcnt vmcnt(0)
	v_pk_mul_f32 v[72:73], v[72:73], v[76:77]
	v_pk_mul_f32 v[74:75], v[74:75], v[78:79]
	global_store_dwordx4 v[146:147], v[72:75], off offset:16
	global_load_dwordx4 v[72:75], v[148:149], off offset:512
	v_pk_mul_f32 v[76:77], v[80:81], v[156:157] op_sel_hi:[1,0]
	v_pk_mul_f32 v[78:79], v[82:83], v[156:157] op_sel_hi:[1,0]
	s_waitcnt vmcnt(0)
	v_pk_mul_f32 v[72:73], v[72:73], v[76:77]
	v_pk_mul_f32 v[74:75], v[74:75], v[78:79]
	global_store_dwordx4 v[146:147], v[72:75], off offset:512
	global_load_dwordx4 v[72:75], v[148:149], off offset:528
	v_pk_mul_f32 v[76:77], v[88:89], v[156:157] op_sel_hi:[1,0]
	v_pk_mul_f32 v[78:79], v[90:91], v[156:157] op_sel_hi:[1,0]
	s_waitcnt vmcnt(0)
	v_pk_mul_f32 v[72:73], v[76:77], v[72:73]
	v_pk_mul_f32 v[74:75], v[78:79], v[74:75]
	global_store_dwordx4 v[146:147], v[72:75], off offset:528
	global_load_dword v76, v[160:161], off sc1
	s_nop 0
	global_load_dwordx4 v[72:75], v[148:149], off
	v_lshlrev_b64 v[78:79], 13, v[150:151]
	v_lshl_add_u64 v[78:79], s[90:91], 0, v[78:79]
	v_lshl_add_u64 v[78:79], v[78:79], 0, v[154:155]
	s_waitcnt vmcnt(1)
	v_fmamk_f32 v76, v76, 0x3a000000, v189
	v_rsq_f32_e32 v76, v76
	s_nop 0
	v_pk_mul_f32 v[80:81], v[96:97], v[76:77] op_sel_hi:[1,0]
	v_pk_mul_f32 v[82:83], v[98:99], v[76:77] op_sel_hi:[1,0]
	s_waitcnt vmcnt(0)
	v_pk_mul_f32 v[72:73], v[72:73], v[80:81]
	v_pk_mul_f32 v[74:75], v[74:75], v[82:83]
	global_store_dwordx4 v[78:79], v[72:75], off
	global_load_dwordx4 v[72:75], v[148:149], off offset:16
	v_pk_mul_f32 v[80:81], v[100:101], v[76:77] op_sel_hi:[1,0]
	v_pk_mul_f32 v[82:83], v[102:103], v[76:77] op_sel_hi:[1,0]
	s_waitcnt vmcnt(0)
	v_pk_mul_f32 v[72:73], v[72:73], v[80:81]
	v_pk_mul_f32 v[74:75], v[74:75], v[82:83]
	global_store_dwordx4 v[78:79], v[72:75], off offset:16
	global_load_dwordx4 v[72:75], v[148:149], off offset:512
	v_pk_mul_f32 v[80:81], v[108:109], v[76:77] op_sel_hi:[1,0]
	v_pk_mul_f32 v[82:83], v[110:111], v[76:77] op_sel_hi:[1,0]
	s_waitcnt vmcnt(0)
	v_pk_mul_f32 v[72:73], v[72:73], v[80:81]
	v_pk_mul_f32 v[74:75], v[74:75], v[82:83]
	global_store_dwordx4 v[78:79], v[72:75], off offset:512
	global_load_dwordx4 v[72:75], v[148:149], off offset:528
	v_pk_mul_f32 v[80:81], v[112:113], v[76:77] op_sel_hi:[1,0]
	v_pk_mul_f32 v[76:77], v[114:115], v[76:77] op_sel_hi:[1,0]
	s_waitcnt vmcnt(0)
	v_pk_mul_f32 v[72:73], v[80:81], v[72:73]
	v_pk_mul_f32 v[74:75], v[76:77], v[74:75]
	global_store_dwordx4 v[78:79], v[72:75], off offset:528
	global_load_dword v76, v[166:167], off sc1
	s_nop 0
	global_load_dwordx4 v[72:75], v[148:149], off
	v_lshlrev_b64 v[78:79], 13, v[152:153]
	v_lshl_add_u64 v[78:79], s[90:91], 0, v[78:79]
	v_lshl_add_u64 v[78:79], v[78:79], 0, v[154:155]
	s_waitcnt vmcnt(1)
	v_fmamk_f32 v76, v76, 0x3a000000, v189
	v_rsq_f32_e32 v76, v76
	s_nop 0
	v_pk_mul_f32 v[80:81], v[120:121], v[76:77] op_sel_hi:[1,0]
	v_pk_mul_f32 v[82:83], v[122:123], v[76:77] op_sel_hi:[1,0]
	s_waitcnt vmcnt(0)
	v_pk_mul_f32 v[72:73], v[72:73], v[80:81]
	v_pk_mul_f32 v[74:75], v[74:75], v[82:83]
	global_store_dwordx4 v[78:79], v[72:75], off
	global_load_dwordx4 v[72:75], v[148:149], off offset:16
	v_pk_mul_f32 v[80:81], v[124:125], v[76:77] op_sel_hi:[1,0]
	v_pk_mul_f32 v[82:83], v[126:127], v[76:77] op_sel_hi:[1,0]
	s_waitcnt vmcnt(0)
	v_pk_mul_f32 v[72:73], v[72:73], v[80:81]
	v_pk_mul_f32 v[74:75], v[74:75], v[82:83]
	global_store_dwordx4 v[78:79], v[72:75], off offset:16
	global_load_dwordx4 v[72:75], v[148:149], off offset:512
	v_pk_mul_f32 v[80:81], v[116:117], v[76:77] op_sel_hi:[1,0]
	v_pk_mul_f32 v[82:83], v[118:119], v[76:77] op_sel_hi:[1,0]
	s_waitcnt vmcnt(0)
	v_pk_mul_f32 v[72:73], v[72:73], v[80:81]
	v_pk_mul_f32 v[74:75], v[74:75], v[82:83]
	global_store_dwordx4 v[78:79], v[72:75], off offset:512
	global_load_dwordx4 v[72:75], v[148:149], off offset:528
	v_pk_mul_f32 v[80:81], v[104:105], v[76:77] op_sel_hi:[1,0]
	v_pk_mul_f32 v[76:77], v[106:107], v[76:77] op_sel_hi:[1,0]
	s_waitcnt vmcnt(0)
	v_pk_mul_f32 v[72:73], v[80:81], v[72:73]
	v_pk_mul_f32 v[74:75], v[76:77], v[74:75]
	global_store_dwordx4 v[78:79], v[72:75], off offset:528
	global_load_dword v76, v[170:171], off sc1
	s_nop 0
	global_load_dwordx4 v[72:75], v[148:149], off
	v_lshlrev_b64 v[78:79], 13, v[158:159]
	v_lshl_add_u64 v[78:79], s[90:91], 0, v[78:79]
	v_lshl_add_u64 v[78:79], v[78:79], 0, v[154:155]
	s_waitcnt vmcnt(1)
	v_fmamk_f32 v76, v76, 0x3a000000, v189
	v_rsq_f32_e32 v76, v76
	s_nop 0
	v_pk_mul_f32 v[80:81], v[92:93], v[76:77] op_sel_hi:[1,0]
	v_pk_mul_f32 v[82:83], v[94:95], v[76:77] op_sel_hi:[1,0]
	s_waitcnt vmcnt(0)
	v_pk_mul_f32 v[72:73], v[72:73], v[80:81]
	v_pk_mul_f32 v[74:75], v[74:75], v[82:83]
	global_store_dwordx4 v[78:79], v[72:75], off
	global_load_dwordx4 v[72:75], v[148:149], off offset:16
	v_pk_mul_f32 v[80:81], v[84:85], v[76:77] op_sel_hi:[1,0]
	v_pk_mul_f32 v[82:83], v[86:87], v[76:77] op_sel_hi:[1,0]
	v_pk_mul_f32 v[68:69], v[68:69], v[76:77] op_sel_hi:[1,0]
	v_pk_mul_f32 v[70:71], v[70:71], v[76:77] op_sel_hi:[1,0]
	v_pk_mul_f32 v[64:65], v[64:65], v[76:77] op_sel_hi:[1,0]
	v_pk_mul_f32 v[66:67], v[66:67], v[76:77] op_sel_hi:[1,0]
	s_waitcnt vmcnt(0)
	v_pk_mul_f32 v[74:75], v[74:75], v[82:83]
	v_pk_mul_f32 v[72:73], v[72:73], v[80:81]
	global_store_dwordx4 v[78:79], v[72:75], off offset:16
	global_load_dwordx4 v[72:75], v[148:149], off offset:512
	s_waitcnt vmcnt(0)
	v_pk_mul_f32 v[70:71], v[74:75], v[70:71]
	v_pk_mul_f32 v[68:69], v[72:73], v[68:69]
	global_store_dwordx4 v[78:79], v[68:71], off offset:512
	global_load_dwordx4 v[68:71], v[148:149], off offset:528
	s_waitcnt vmcnt(0)
	v_pk_mul_f32 v[66:67], v[66:67], v[70:71]
	v_pk_mul_f32 v[64:65], v[64:65], v[68:69]
	global_store_dwordx4 v[78:79], v[64:67], off offset:528
	global_load_dword v68, v[144:145], off offset:512 sc1
	s_nop 0
	global_load_dwordx4 v[64:67], v[148:149], off
	v_lshlrev_b64 v[70:71], 13, v[164:165]
	v_lshl_add_u64 v[70:71], s[90:91], 0, v[70:71]
	v_lshl_add_u64 v[70:71], v[70:71], 0, v[154:155]
	s_waitcnt vmcnt(1)
	v_fmamk_f32 v68, v68, 0x3a000000, v189
	v_rsq_f32_e32 v68, v68
	s_nop 0
	v_pk_mul_f32 v[60:61], v[60:61], v[68:69] op_sel_hi:[1,0]
	v_pk_mul_f32 v[62:63], v[62:63], v[68:69] op_sel_hi:[1,0]
	s_waitcnt vmcnt(0)
	v_pk_mul_f32 v[60:61], v[64:65], v[60:61]
	v_pk_mul_f32 v[62:63], v[66:67], v[62:63]
	global_store_dwordx4 v[70:71], v[60:63], off
	global_load_dwordx4 v[60:63], v[148:149], off offset:16
	v_pk_mul_f32 v[56:57], v[56:57], v[68:69] op_sel_hi:[1,0]
	v_pk_mul_f32 v[58:59], v[58:59], v[68:69] op_sel_hi:[1,0]
	v_pk_mul_f32 v[52:53], v[52:53], v[68:69] op_sel_hi:[1,0]
	v_pk_mul_f32 v[54:55], v[54:55], v[68:69] op_sel_hi:[1,0]
	v_pk_mul_f32 v[48:49], v[48:49], v[68:69] op_sel_hi:[1,0]
	v_pk_mul_f32 v[50:51], v[50:51], v[68:69] op_sel_hi:[1,0]
	s_waitcnt vmcnt(0)
	v_pk_mul_f32 v[58:59], v[62:63], v[58:59]
	v_pk_mul_f32 v[56:57], v[60:61], v[56:57]
	global_store_dwordx4 v[70:71], v[56:59], off offset:16
	global_load_dwordx4 v[56:59], v[148:149], off offset:512
	s_waitcnt vmcnt(0)
	v_pk_mul_f32 v[54:55], v[58:59], v[54:55]
	v_pk_mul_f32 v[52:53], v[56:57], v[52:53]
	global_store_dwordx4 v[70:71], v[52:55], off offset:512
	global_load_dwordx4 v[52:55], v[148:149], off offset:528
	s_waitcnt vmcnt(0)
	v_pk_mul_f32 v[50:51], v[50:51], v[54:55]
	v_pk_mul_f32 v[48:49], v[48:49], v[52:53]
	global_store_dwordx4 v[70:71], v[48:51], off offset:528
	global_load_dword v52, v[144:145], off offset:576 sc1
	s_nop 0
	global_load_dwordx4 v[48:51], v[148:149], off
	v_lshlrev_b64 v[54:55], 13, v[168:169]
	v_lshl_add_u64 v[54:55], s[90:91], 0, v[54:55]
	v_lshl_add_u64 v[54:55], v[54:55], 0, v[154:155]
	s_waitcnt vmcnt(1)
	v_fmamk_f32 v52, v52, 0x3a000000, v189
	v_rsq_f32_e32 v52, v52
	s_nop 0
	v_pk_mul_f32 v[44:45], v[44:45], v[52:53] op_sel_hi:[1,0]
	v_pk_mul_f32 v[46:47], v[46:47], v[52:53] op_sel_hi:[1,0]
	s_waitcnt vmcnt(0)
	v_pk_mul_f32 v[44:45], v[48:49], v[44:45]
	v_pk_mul_f32 v[46:47], v[50:51], v[46:47]
	global_store_dwordx4 v[54:55], v[44:47], off
	global_load_dwordx4 v[44:47], v[148:149], off offset:16
	v_pk_mul_f32 v[40:41], v[40:41], v[52:53] op_sel_hi:[1,0]
	v_pk_mul_f32 v[42:43], v[42:43], v[52:53] op_sel_hi:[1,0]
	v_pk_mul_f32 v[36:37], v[36:37], v[52:53] op_sel_hi:[1,0]
	v_pk_mul_f32 v[38:39], v[38:39], v[52:53] op_sel_hi:[1,0]
	v_pk_mul_f32 v[32:33], v[32:33], v[52:53] op_sel_hi:[1,0]
	v_pk_mul_f32 v[34:35], v[34:35], v[52:53] op_sel_hi:[1,0]
	s_waitcnt vmcnt(0)
	v_pk_mul_f32 v[42:43], v[46:47], v[42:43]
	v_pk_mul_f32 v[40:41], v[44:45], v[40:41]
	global_store_dwordx4 v[54:55], v[40:43], off offset:16
	global_load_dwordx4 v[40:43], v[148:149], off offset:512
	s_waitcnt vmcnt(0)
	v_pk_mul_f32 v[38:39], v[42:43], v[38:39]
	v_pk_mul_f32 v[36:37], v[40:41], v[36:37]
	global_store_dwordx4 v[54:55], v[36:39], off offset:512
	global_load_dwordx4 v[36:39], v[148:149], off offset:528
	s_waitcnt vmcnt(0)
	v_pk_mul_f32 v[34:35], v[34:35], v[38:39]
	v_pk_mul_f32 v[32:33], v[32:33], v[36:37]
	global_store_dwordx4 v[54:55], v[32:35], off offset:528
	global_load_dword v36, v[144:145], off offset:640 sc1
	s_nop 0
	global_load_dwordx4 v[32:35], v[148:149], off
	v_lshlrev_b64 v[38:39], 13, v[172:173]
	v_lshl_add_u64 v[38:39], s[90:91], 0, v[38:39]
	v_lshl_add_u64 v[38:39], v[38:39], 0, v[154:155]
	s_waitcnt vmcnt(1)
	v_fmamk_f32 v36, v36, 0x3a000000, v189
	v_rsq_f32_e32 v36, v36
	s_nop 0
	v_pk_mul_f32 v[28:29], v[28:29], v[36:37] op_sel_hi:[1,0]
	v_pk_mul_f32 v[30:31], v[30:31], v[36:37] op_sel_hi:[1,0]
	s_waitcnt vmcnt(0)
	v_pk_mul_f32 v[28:29], v[32:33], v[28:29]
	v_pk_mul_f32 v[30:31], v[34:35], v[30:31]
	global_store_dwordx4 v[38:39], v[28:31], off
	global_load_dwordx4 v[28:31], v[148:149], off offset:16
	v_pk_mul_f32 v[24:25], v[24:25], v[36:37] op_sel_hi:[1,0]
	v_pk_mul_f32 v[26:27], v[26:27], v[36:37] op_sel_hi:[1,0]
	v_pk_mul_f32 v[20:21], v[20:21], v[36:37] op_sel_hi:[1,0]
	v_pk_mul_f32 v[22:23], v[22:23], v[36:37] op_sel_hi:[1,0]
	v_pk_mul_f32 v[16:17], v[16:17], v[36:37] op_sel_hi:[1,0]
	v_pk_mul_f32 v[18:19], v[18:19], v[36:37] op_sel_hi:[1,0]
	s_waitcnt vmcnt(0)
	v_pk_mul_f32 v[26:27], v[30:31], v[26:27]
	v_pk_mul_f32 v[24:25], v[28:29], v[24:25]
	global_store_dwordx4 v[38:39], v[24:27], off offset:16
	global_load_dwordx4 v[24:27], v[148:149], off offset:512
	s_waitcnt vmcnt(0)
	v_pk_mul_f32 v[22:23], v[26:27], v[22:23]
	v_pk_mul_f32 v[20:21], v[24:25], v[20:21]
	global_store_dwordx4 v[38:39], v[20:23], off offset:512
	global_load_dwordx4 v[20:23], v[148:149], off offset:528
	s_waitcnt vmcnt(0)
	v_pk_mul_f32 v[18:19], v[18:19], v[22:23]
	v_pk_mul_f32 v[16:17], v[16:17], v[20:21]
	global_store_dwordx4 v[38:39], v[16:19], off offset:528
	global_load_dword v20, v[144:145], off offset:704 sc1
	s_nop 0
	global_load_dwordx4 v[16:19], v[148:149], off
	v_lshlrev_b64 v[22:23], 13, v[174:175]
	v_lshl_add_u64 v[22:23], s[90:91], 0, v[22:23]
	v_lshl_add_u64 v[22:23], v[22:23], 0, v[154:155]
	s_waitcnt vmcnt(1)
	v_fmamk_f32 v20, v20, 0x3a000000, v189
	v_rsq_f32_e32 v20, v20
	s_nop 0
	v_pk_mul_f32 v[12:13], v[12:13], v[20:21] op_sel_hi:[1,0]
	v_pk_mul_f32 v[14:15], v[14:15], v[20:21] op_sel_hi:[1,0]
	s_waitcnt vmcnt(0)
	v_pk_mul_f32 v[12:13], v[16:17], v[12:13]
	v_pk_mul_f32 v[14:15], v[18:19], v[14:15]
	global_store_dwordx4 v[22:23], v[12:15], off
	global_load_dwordx4 v[12:15], v[148:149], off offset:16
	v_pk_mul_f32 v[8:9], v[8:9], v[20:21] op_sel_hi:[1,0]
	v_pk_mul_f32 v[10:11], v[10:11], v[20:21] op_sel_hi:[1,0]
	v_pk_mul_f32 v[4:5], v[4:5], v[20:21] op_sel_hi:[1,0]
	v_pk_mul_f32 v[6:7], v[6:7], v[20:21] op_sel_hi:[1,0]
	v_pk_mul_f32 v[0:1], v[0:1], v[20:21] op_sel_hi:[1,0]
	v_pk_mul_f32 v[2:3], v[2:3], v[20:21] op_sel_hi:[1,0]
	s_waitcnt vmcnt(0)
	v_pk_mul_f32 v[10:11], v[14:15], v[10:11]
	v_pk_mul_f32 v[8:9], v[12:13], v[8:9]
	global_store_dwordx4 v[22:23], v[8:11], off offset:16
	global_load_dwordx4 v[8:11], v[148:149], off offset:512
	s_waitcnt vmcnt(0)
	v_pk_mul_f32 v[6:7], v[10:11], v[6:7]
	v_pk_mul_f32 v[4:5], v[8:9], v[4:5]
	global_store_dwordx4 v[22:23], v[4:7], off offset:512
	global_load_dwordx4 v[4:7], v[148:149], off offset:528
	s_waitcnt vmcnt(0)
	v_pk_mul_f32 v[2:3], v[2:3], v[6:7]
	v_pk_mul_f32 v[0:1], v[0:1], v[4:5]
	global_store_dwordx4 v[22:23], v[0:3], off offset:528
	s_and_b64 vcc, exec, s[44:45]
	s_mov_b64 s[22:23], -1
	s_cbranch_vccnz .LBB0_928
